# v23 + the deferred retc->in-proj barrier wait no longer invalidates caches in the middle of the first in-proj tile (every consumer of pre-barrier data is behind a later invalidate)
# baseline (speedup 1.0000x reference)
; __device__ __forceinline__ unsigned xb_ld(unsigned* p)              { return __hip_atomic_load(p, __ATOMIC_RELAXED, __HIP_MEMORY_SCOPE_AGENT); }
; #define XB_SPIN(cond, bar) do { unsigned _sp = 0; while (cond) { __builtin_amdgcn_s_sleep(1); \
;     if ((++_sp & 255u) == 0u) { if (xb_ld(&(bar)[XB_TMO])) break; if (_sp > XB_SPIN_CAP) { atomicAdd(&(bar)[XB_TMO], 1u); break; } } } } while (0)
; __device__ __forceinline__ void xcd_barrier(const int wv, const XcdBarrier& b) {
;     ...
;             asm volatile("s_waitcnt vmcnt(0)" ::: "memory");
;         } else {
;             XB_SPIN(xb_ld(&bar[XB_XGEN(b.x)]) == gen, bar);
;             __builtin_amdgcn_fence(__ATOMIC_ACQUIRE, "agent");
;             asm volatile("s_waitcnt vmcnt(0)" ::: "memory");
;         }
.Lgwip_got:
	s_waitcnt vmcnt(0)
	s_mov_b32 s101, 0
